# in-projection z tiles stored with nt (keep XBCP cache-resident for the conv phase)
# speedup vs baseline: 1.0045x; 1.0015x over previous
; #define PG8_STAGE(bufoff, gbase, voff) do { _Pragma("unroll") for (int _i = 0; _i < 2; ++_i) \
;         __builtin_amdgcn_global_load_lds((const unsigned*)((const char*)(gbase) + (voff)[_i]), (LAS unsigned*)(lds + (bufoff) + ldsw + _i * 8192), 16, 0, 0); } while (0)
; #define PG8_LDA(dst, b, h) do { _Pragma("unroll") for (int m = 0; m < 4; ++m) _Pragma("unroll") for (int k = 0; k < 2; ++k) dst[m][k] = *(const LAS bf16x8*)(lds + PG8_SA(b, h) + aoff + m * 2048 + k * 1024); } while (0)
; #define PG8_LDB(dst, b, h) do { _Pragma("unroll") for (int n = 0; n < 2; ++n) _Pragma("unroll") for (int k = 0; k < 2; ++k) dst[n][k] = *(const LAS bf16x8*)(lds + PG8_SB(b, h) + boff + n * 2048 + k * 1024); } while (0)
; #define PG8_MMA(ai, bj, At, Bt) do { __builtin_amdgcn_s_setprio(1); _Pragma("unroll") for (int m = 0; m < 4; ++m) _Pragma("unroll") for (int n = 0; n < 2; ++n) _Pragma("unroll") for (int k = 0; k < 2; ++k) \
;         acc[ai][bj][m][n] = __builtin_amdgcn_mfma_f32_16x16x32_bf16(Bt[n][k], At[m][k], acc[ai][bj][m][n], 0, 0, 0); __builtin_amdgcn_s_setprio(0); } while (0)
; #define PG8_WAIT_V(n) asm volatile("s_waitcnt vmcnt(" #n ")" ::: "memory")
; #define PG8_WAIT_L(n) asm volatile("s_waitcnt lgkmcnt(" #n ")" ::: "memory")
; #define PG8_BAR __builtin_amdgcn_s_barrier()
; #define PG8_SCHED __builtin_amdgcn_sched_barrier(0)
; template <class Epi, class Sched, bool ALIGN_EPI>
; __device__ __forceinline__ void gemm_phase(LAS unsigned char* lds, const int wid, const int lda_, const int ldb_, const int K_, const Sched& S, const Epi& E) {
;     ...
;             PG8_LDB(B0, 1, 0); PG8_LDB(B1, 1, 1); PG8_SCHED; PG8_LDA(At, 1, 0); PG8_STAGE(PG8_SA(0, 1), a2 + hstepA, voffA);
;             PG8_WAIT_V(8); PG8_WAIT_L(0); PG8_BAR; PG8_MMA(0, 0, At, B0); PG8_MMA(0, 1, At, B1); PG8_BAR; PG8_SCHED;
.Lgemm_join_299:
	s_add_i32 s17, 0, 0x18000
	v_add_u32_e32 v141, s17, v135
	s_add_i32 s27, 0, 0x1c000
	ds_read_b128 v[160:163], v141
	ds_read_b128 v[164:167], v141 offset:1024
	ds_read_b128 v[168:171], v141 offset:2048
	ds_read_b128 v[172:175], v141 offset:3072
	v_add_u32_e32 v141, s27, v135
	ds_read_b128 v[180:183], v141
	ds_read_b128 v[184:187], v141 offset:1024
	ds_read_b128 v[188:191], v141 offset:2048
	ds_read_b128 v[192:195], v141 offset:3072
	s_add_u32 s50, s50, s0
	s_addc_u32 s51, s51, s1
	s_mov_b32 m0, s26
	v_lshl_add_u64 v[248:249], s[50:51], 0, v[132:133]
	ds_read_b128 v[196:199], v139 offset:32768
	ds_read_b128 v[200:203], v139 offset:33792
	ds_read_b128 v[204:207], v139 offset:34816
	ds_read_b128 v[208:211], v139 offset:35840
	ds_read_b128 v[212:215], v139 offset:36864
	ds_read_b128 v[216:219], v139 offset:37888
	ds_read_b128 v[220:223], v139 offset:38912
	ds_read_b128 v[224:227], v139 offset:39936
	global_load_lds_dwordx4 v[248:249], off
	v_lshl_add_u64 v[248:249], s[50:51], 0, v[130:131]
	s_mov_b32 m0, s72
	s_nop 0
	global_load_lds_dwordx4 v[248:249], off
	s_waitcnt vmcnt(8)
	s_waitcnt lgkmcnt(0)
	s_barrier
	s_setprio 1
	s_waitcnt lgkmcnt(0)
	v_mfma_f32_16x16x32_bf16 v[124:127], v[160:163], v[196:199], v[124:127]
	v_mfma_f32_16x16x32_bf16 v[120:123], v[168:171], v[196:199], v[120:123]
	v_mfma_f32_16x16x32_bf16 v[116:119], v[160:163], v[204:207], v[116:119]
	v_mfma_f32_16x16x32_bf16 v[112:115], v[168:171], v[204:207], v[112:115]
	v_mfma_f32_16x16x32_bf16 v[100:103], v[160:163], v[212:215], v[100:103]
	v_mfma_f32_16x16x32_bf16 v[96:99], v[168:171], v[212:215], v[96:99]
	v_mfma_f32_16x16x32_bf16 v[84:87], v[160:163], v[220:223], v[84:87]
	v_mfma_f32_16x16x32_bf16 v[80:83], v[168:171], v[220:223], v[80:83]
	v_mfma_f32_16x16x32_bf16 v[124:127], v[164:167], v[200:203], v[124:127]
	v_mfma_f32_16x16x32_bf16 v[120:123], v[172:175], v[200:203], v[120:123]
	v_mfma_f32_16x16x32_bf16 v[116:119], v[164:167], v[208:211], v[116:119]
	v_mfma_f32_16x16x32_bf16 v[112:115], v[172:175], v[208:211], v[112:115]
	v_mfma_f32_16x16x32_bf16 v[100:103], v[164:167], v[216:219], v[100:103]
	v_mfma_f32_16x16x32_bf16 v[96:99], v[172:175], v[216:219], v[96:99]
	v_mfma_f32_16x16x32_bf16 v[84:87], v[164:167], v[224:227], v[84:87]
	v_mfma_f32_16x16x32_bf16 v[80:83], v[172:175], v[224:227], v[80:83]
	s_setprio 0
	s_setprio 1
	v_mfma_f32_16x16x32_bf16 v[108:111], v[180:183], v[196:199], v[108:111]
	v_mfma_f32_16x16x32_bf16 v[104:107], v[188:191], v[196:199], v[104:107]
	v_mfma_f32_16x16x32_bf16 v[92:95], v[180:183], v[204:207], v[92:95]
	v_mfma_f32_16x16x32_bf16 v[88:91], v[188:191], v[204:207], v[88:91]
	v_mfma_f32_16x16x32_bf16 v[76:79], v[180:183], v[212:215], v[76:79]
	v_mfma_f32_16x16x32_bf16 v[72:75], v[188:191], v[212:215], v[72:75]
	v_mfma_f32_16x16x32_bf16 v[68:71], v[180:183], v[220:223], v[68:71]
	v_mfma_f32_16x16x32_bf16 v[64:67], v[188:191], v[220:223], v[64:67]
	v_mfma_f32_16x16x32_bf16 v[108:111], v[184:187], v[200:203], v[108:111]
	v_mfma_f32_16x16x32_bf16 v[104:107], v[192:195], v[200:203], v[104:107]
	v_mfma_f32_16x16x32_bf16 v[92:95], v[184:187], v[208:211], v[92:95]
	v_mfma_f32_16x16x32_bf16 v[88:91], v[192:195], v[208:211], v[88:91]
	v_mfma_f32_16x16x32_bf16 v[76:79], v[184:187], v[216:219], v[76:79]
	v_mfma_f32_16x16x32_bf16 v[72:75], v[192:195], v[216:219], v[72:75]
	v_mfma_f32_16x16x32_bf16 v[68:71], v[184:187], v[224:227], v[68:71]
	v_mfma_f32_16x16x32_bf16 v[64:67], v[192:195], v[224:227], v[64:67]
	s_setprio 0
	s_barrier
; #define PG8_STAGE(bufoff, gbase, voff) do { _Pragma("unroll") for (int _i = 0; _i < 2; ++_i) \
;         __builtin_amdgcn_global_load_lds((const unsigned*)((const char*)(gbase) + (voff)[_i]), (LAS unsigned*)(lds + (bufoff) + ldsw + _i * 8192), 16, 0, 0); } while (0)
; #define PG8_LDA(dst, b, h) do { _Pragma("unroll") for (int m = 0; m < 4; ++m) _Pragma("unroll") for (int k = 0; k < 2; ++k) dst[m][k] = *(const LAS bf16x8*)(lds + PG8_SA(b, h) + aoff + m * 2048 + k * 1024); } while (0)
; #define PG8_MMA(ai, bj, At, Bt) do { __builtin_amdgcn_s_setprio(1); _Pragma("unroll") for (int m = 0; m < 4; ++m) _Pragma("unroll") for (int n = 0; n < 2; ++n) _Pragma("unroll") for (int k = 0; k < 2; ++k) \
;         acc[ai][bj][m][n] = __builtin_amdgcn_mfma_f32_16x16x32_bf16(Bt[n][k], At[m][k], acc[ai][bj][m][n], 0, 0, 0); __builtin_amdgcn_s_setprio(0); } while (0)
; #define PG8_WAIT_V(n) asm volatile("s_waitcnt vmcnt(" #n ")" ::: "memory")
; #define PG8_WAIT_L(n) asm volatile("s_waitcnt lgkmcnt(" #n ")" ::: "memory")
; #define PG8_BAR __builtin_amdgcn_s_barrier()
; #define PG8_SCHED __builtin_amdgcn_sched_barrier(0)
; template <class Epi, class Sched, bool ALIGN_EPI>
; __device__ __forceinline__ void gemm_phase(LAS unsigned char* lds, const int wid, const int lda_, const int ldb_, const int K_, const Sched& S, const Epi& E) {
;     ...
;             PG8_LDA(At, 1, 1); PG8_STAGE(PG8_SB(1, 0), b3, voffB); PG8_STAGE(PG8_SB(1, 1), b3 + hstepB, voffB); PG8_STAGE(PG8_SA(1, 0), a3, voffA);
;             PG8_WAIT_V(8); PG8_WAIT_L(0); PG8_BAR; PG8_MMA(1, 0, At, B0); PG8_MMA(1, 1, At, B1); PG8_BAR; PG8_SCHED;
;     __device__ __forceinline__ void out(const pg8::Unit& u, char*& o, int& ldo, int& kind) const {
;         if (u.pn < 24) { o = (char*)ws + WS_XBCP + ((size_t)u.pm * 256 * XBC + (size_t)u.pn * 256) * 2; ldo = XBC; kind = 0; }
;         else if (u.pn < 40) { o = (char*)ws + WS_Z + ((size_t)u.pm * 256 * DI + (size_t)(u.pn - 24) * 256) * 2; ldo = DI; kind = 0; }
;         else { o = (char*)ws + WS_DT + (size_t)u.pm * 256 * 128 * 4; ldo = 128; kind = 1; } }
	s_add_i32 s17, s17, s3
	v_lshl_add_u64 v[228:229], v[228:229], 0, s[24:25]
	s_mov_b32 m0, s17
	ds_read_b128 v[196:199], v139 offset:49152
	ds_read_b128 v[200:203], v139 offset:50176
	ds_read_b128 v[204:207], v139 offset:51200
	ds_read_b128 v[208:211], v139 offset:52224
	ds_read_b128 v[212:215], v139 offset:53248
	ds_read_b128 v[216:219], v139 offset:54272
	ds_read_b128 v[220:223], v139 offset:55296
	ds_read_b128 v[224:227], v139 offset:56320
	global_load_lds_dwordx4 v[228:229], off
	v_lshl_add_u64 v[228:229], v[230:231], 0, s[24:25]
	s_add_i32 m0, s17, 0x2000
	s_add_i32 s17, s27, s3
	global_load_lds_dwordx4 v[228:229], off
	v_lshl_add_u64 v[228:229], v[232:233], 0, s[24:25]
	s_mov_b32 m0, s17
	s_nop 0
	global_load_lds_dwordx4 v[228:229], off
	v_lshl_add_u64 v[228:229], v[234:235], 0, s[24:25]
	s_add_i32 m0, s17, 0x2000
	s_nop 0
	global_load_lds_dwordx4 v[228:229], off
	v_lshl_add_u64 v[228:229], v[236:237], 0, s[24:25]
	s_mov_b32 m0, s73
	s_nop 0
	global_load_lds_dwordx4 v[228:229], off
	v_lshl_add_u64 v[228:229], v[246:247], 0, s[24:25]
	s_mov_b32 m0, s74
	s_nop 0
	global_load_lds_dwordx4 v[228:229], off
	s_waitcnt vmcnt(8)
	s_waitcnt lgkmcnt(0)
	s_barrier
	s_setprio 1
	s_waitcnt lgkmcnt(0)
	v_mfma_f32_16x16x32_bf16 v[60:63], v[160:163], v[196:199], v[60:63]
	v_mfma_f32_16x16x32_bf16 v[56:59], v[168:171], v[196:199], v[56:59]
	v_mfma_f32_16x16x32_bf16 v[52:55], v[160:163], v[204:207], v[52:55]
	v_mfma_f32_16x16x32_bf16 v[48:51], v[168:171], v[204:207], v[48:51]
	v_mfma_f32_16x16x32_bf16 v[36:39], v[160:163], v[212:215], v[36:39]
	v_mfma_f32_16x16x32_bf16 v[32:35], v[168:171], v[212:215], v[32:35]
	v_mfma_f32_16x16x32_bf16 v[20:23], v[160:163], v[220:223], v[20:23]
	v_mfma_f32_16x16x32_bf16 v[16:19], v[168:171], v[220:223], v[16:19]
	v_mfma_f32_16x16x32_bf16 v[60:63], v[164:167], v[200:203], v[60:63]
	v_mfma_f32_16x16x32_bf16 v[56:59], v[172:175], v[200:203], v[56:59]
	v_mfma_f32_16x16x32_bf16 v[52:55], v[164:167], v[208:211], v[52:55]
	v_mfma_f32_16x16x32_bf16 v[48:51], v[172:175], v[208:211], v[48:51]
	v_mfma_f32_16x16x32_bf16 v[36:39], v[164:167], v[216:219], v[36:39]
	v_mfma_f32_16x16x32_bf16 v[32:35], v[172:175], v[216:219], v[32:35]
	v_mfma_f32_16x16x32_bf16 v[20:23], v[164:167], v[224:227], v[20:23]
	v_mfma_f32_16x16x32_bf16 v[16:19], v[172:175], v[224:227], v[16:19]
	s_setprio 0
	s_setprio 1
	v_mfma_f32_16x16x32_bf16 v[44:47], v[180:183], v[196:199], v[44:47]
	v_mfma_f32_16x16x32_bf16 v[40:43], v[188:191], v[196:199], v[40:43]
	v_mfma_f32_16x16x32_bf16 v[28:31], v[180:183], v[204:207], v[28:31]
	v_mfma_f32_16x16x32_bf16 v[24:27], v[188:191], v[204:207], v[24:27]
	v_mfma_f32_16x16x32_bf16 v[12:15], v[180:183], v[212:215], v[12:15]
	v_mfma_f32_16x16x32_bf16 v[8:11], v[188:191], v[212:215], v[8:11]
	v_mfma_f32_16x16x32_bf16 v[4:7], v[180:183], v[220:223], v[4:7]
	v_mfma_f32_16x16x32_bf16 v[0:3], v[188:191], v[220:223], v[0:3]
	v_mfma_f32_16x16x32_bf16 v[44:47], v[184:187], v[200:203], v[44:47]
	v_mfma_f32_16x16x32_bf16 v[40:43], v[192:195], v[200:203], v[40:43]
	v_mfma_f32_16x16x32_bf16 v[28:31], v[184:187], v[208:211], v[28:31]
	v_mfma_f32_16x16x32_bf16 v[24:27], v[192:195], v[208:211], v[24:27]
	v_mfma_f32_16x16x32_bf16 v[12:15], v[184:187], v[216:219], v[12:15]
	v_mfma_f32_16x16x32_bf16 v[8:11], v[192:195], v[216:219], v[8:11]
	v_mfma_f32_16x16x32_bf16 v[4:7], v[184:187], v[224:227], v[4:7]
	v_mfma_f32_16x16x32_bf16 v[0:3], v[192:195], v[224:227], v[0:3]
	s_setprio 0
	s_barrier
	s_add_i32 s76, s76, 2
	s_add_u32 s48, s48, 0x100
	s_addc_u32 s49, s49, 0
	s_cmp_gt_u32 s76, 29
	s_cbranch_scc0 .LBB0_299
	s_setprio 2
	s_sub_u32 s100, s30, 24
	s_cmp_lt_u32 s100, 16
	s_cselect_b32 s100, 1, 0
	s_ashr_i32 s45, s44, 31
	s_cmp_gt_i32 s30, 23
	s_mov_b64 s[48:49], -1
	s_cbranch_scc0 .LBB0_305
	s_cmp_gt_u32 s30, 39
	s_mov_b64 s[4:5], -1
	s_cbranch_scc0 .LBB0_303
	s_lshl_b64 s[4:5], s[44:45], 17
	v_readlane_b32 s46, v252, 60
	v_readlane_b32 s47, v252, 61
	s_add_u32 s46, s46, s4
	s_addc_u32 s47, s47, s5
	s_mov_b64 s[4:5], 0

; __device__ __forceinline__ unsigned cvt_pk_bf16(float lo, float hi) { const f32x2 v = {lo, hi}; return __builtin_bit_cast(unsigned, __builtin_convertvector(v, bf16x2_t)); }
;     template <class Sched> __device__ __forceinline__ void operator()(const f32x4 (&acc)[2][2][4][2], const Unit& u, const Sched& S, int wr, int wc, int fr, int fq) const {
;     ...
;         if (kind == 0) {
;             bf16_t* base = (bf16_t*)uo;
; #pragma unroll
;             for (int ai = 0; ai < 2; ++ai)
; #pragma unroll
;                 for (int m = 0; m < 4; ++m) { bf16_t* rowp = base + (size_t)(rl0 + ai * HALF + m * 16) * ldo + cl0;
; #pragma unroll
;                     for (int bj = 0; bj < 2; ++bj) { const f32x4 v0 = acc[ai][bj][m][0], v1 = acc[ai][bj][m][1];
;                         u32x4 w; w.x = cvt_pk_bf16(v0[0], v0[1]); w.y = cvt_pk_bf16(v0[2], v0[3]); w.z = cvt_pk_bf16(v1[0], v1[1]); w.w = cvt_pk_bf16(v1[2], v1[3]);
;                         *(u32x4*)(rowp + bj * HALF) = w; } }
.LBB0_309:
	s_andn2_b64 vcc, exec, s[30:31]
	s_cbranch_vccnz .LBB0_292
	s_cmp_lg_u32 s100, 0
	s_cbranch_scc1 .Linproj_epi_nt
	v_lshl_add_u64 v[158:159], v[136:137], 1, s[46:47]
	v_lshl_add_u64 v[156:157], v[156:157], 1, v[158:159]
	v_cvt_pk_bf16_f32 v108, v108, v109
	v_cvt_pk_bf16_f32 v109, v110, v111
	v_cvt_pk_bf16_f32 v110, v104, v105
	v_cvt_pk_bf16_f32 v111, v106, v107
	v_mad_i64_i32 v[104:105], s[4:5], s35, v138, 0
	v_cvt_pk_bf16_f32 v124, v124, v125
	v_cvt_pk_bf16_f32 v125, v126, v127
	v_cvt_pk_bf16_f32 v126, v120, v121
	v_cvt_pk_bf16_f32 v127, v122, v123
	global_store_dwordx4 v[156:157], v[108:111], off offset:256
	v_cvt_pk_bf16_f32 v92, v92, v93
	v_cvt_pk_bf16_f32 v93, v94, v95
	v_lshl_add_u64 v[108:109], v[104:105], 1, v[158:159]
	v_cvt_pk_bf16_f32 v94, v88, v89
	v_cvt_pk_bf16_f32 v95, v90, v91
	v_mad_i64_i32 v[88:89], s[4:5], s35, v140, 0
	global_store_dwordx4 v[156:157], v[124:127], off
	v_cvt_pk_bf16_f32 v104, v116, v117
	v_cvt_pk_bf16_f32 v105, v118, v119
	v_cvt_pk_bf16_f32 v106, v112, v113
	v_cvt_pk_bf16_f32 v107, v114, v115
	global_store_dwordx4 v[108:109], v[92:95], off offset:256
	v_cvt_pk_bf16_f32 v76, v76, v77
	v_cvt_pk_bf16_f32 v77, v78, v79
	v_lshl_add_u64 v[92:93], v[88:89], 1, v[158:159]
	v_cvt_pk_bf16_f32 v78, v72, v73
	v_cvt_pk_bf16_f32 v79, v74, v75
	v_mad_i64_i32 v[72:73], s[4:5], s35, v142, 0
	v_cvt_pk_bf16_f32 v68, v68, v69
	v_cvt_pk_bf16_f32 v69, v70, v71
	v_cvt_pk_bf16_f32 v70, v64, v65
	v_mad_i64_i32 v[64:65], s[4:5], s35, v144, 0
	global_store_dwordx4 v[108:109], v[104:107], off
	v_cvt_pk_bf16_f32 v88, v100, v101
	v_cvt_pk_bf16_f32 v89, v102, v103
	v_cvt_pk_bf16_f32 v90, v96, v97
	v_cvt_pk_bf16_f32 v91, v98, v99
	global_store_dwordx4 v[92:93], v[76:79], off offset:256
	v_cvt_pk_bf16_f32 v74, v80, v81
	v_cvt_pk_bf16_f32 v75, v82, v83
	v_lshl_add_u64 v[76:77], v[72:73], 1, v[158:159]
	v_cvt_pk_bf16_f32 v72, v84, v85
	v_cvt_pk_bf16_f32 v73, v86, v87
	v_cvt_pk_bf16_f32 v71, v66, v67
	v_lshl_add_u64 v[64:65], v[64:65], 1, v[158:159]
	v_cvt_pk_bf16_f32 v44, v44, v45
	v_cvt_pk_bf16_f32 v45, v46, v47
	v_cvt_pk_bf16_f32 v46, v40, v41
	v_cvt_pk_bf16_f32 v47, v42, v43
	v_mad_i64_i32 v[40:41], s[4:5], s35, v146, 0
	global_store_dwordx4 v[92:93], v[88:91], off
	global_store_dwordx4 v[76:77], v[72:75], off
	global_store_dwordx4 v[76:77], v[68:71], off offset:256
	v_cvt_pk_bf16_f32 v60, v60, v61
	v_cvt_pk_bf16_f32 v61, v62, v63
	v_cvt_pk_bf16_f32 v62, v56, v57
	v_cvt_pk_bf16_f32 v63, v58, v59
	global_store_dwordx4 v[64:65], v[44:47], off offset:256
	v_cvt_pk_bf16_f32 v28, v28, v29
	v_cvt_pk_bf16_f32 v29, v30, v31
	v_lshl_add_u64 v[44:45], v[40:41], 1, v[158:159]
	v_cvt_pk_bf16_f32 v30, v24, v25
	v_cvt_pk_bf16_f32 v31, v26, v27
	v_mad_i64_i32 v[24:25], s[4:5], s35, v148, 0
	global_store_dwordx4 v[64:65], v[60:63], off
	v_cvt_pk_bf16_f32 v40, v52, v53
	v_cvt_pk_bf16_f32 v41, v54, v55
	v_cvt_pk_bf16_f32 v42, v48, v49
	v_cvt_pk_bf16_f32 v43, v50, v51
	global_store_dwordx4 v[44:45], v[28:31], off offset:256
	v_cvt_pk_bf16_f32 v12, v12, v13
	v_cvt_pk_bf16_f32 v13, v14, v15
	v_lshl_add_u64 v[28:29], v[24:25], 1, v[158:159]
	v_cvt_pk_bf16_f32 v14, v8, v9
	v_cvt_pk_bf16_f32 v15, v10, v11
	v_mad_i64_i32 v[8:9], s[4:5], s35, v150, 0
	global_store_dwordx4 v[44:45], v[40:43], off
	v_cvt_pk_bf16_f32 v24, v36, v37
	v_cvt_pk_bf16_f32 v25, v38, v39
	v_cvt_pk_bf16_f32 v26, v32, v33
	v_cvt_pk_bf16_f32 v27, v34, v35
	global_store_dwordx4 v[28:29], v[12:15], off offset:256
	v_cvt_pk_bf16_f32 v10, v16, v17
	v_cvt_pk_bf16_f32 v11, v18, v19
	v_lshl_add_u64 v[12:13], v[8:9], 1, v[158:159]
	v_cvt_pk_bf16_f32 v8, v20, v21
	v_cvt_pk_bf16_f32 v9, v22, v23
	v_cvt_pk_bf16_f32 v4, v4, v5
	v_cvt_pk_bf16_f32 v5, v6, v7
	v_cvt_pk_bf16_f32 v6, v0, v1
	v_cvt_pk_bf16_f32 v7, v2, v3
	global_store_dwordx4 v[28:29], v[24:27], off
	global_store_dwordx4 v[12:13], v[8:11], off
	global_store_dwordx4 v[12:13], v[4:7], off offset:256
	s_branch .LBB0_292
; __device__ __forceinline__ unsigned cvt_pk_bf16(float lo, float hi) { const f32x2 v = {lo, hi}; return __builtin_bit_cast(unsigned, __builtin_convertvector(v, bf16x2_t)); }
;     template <class Sched> __device__ __forceinline__ void operator()(const f32x4 (&acc)[2][2][4][2], const Unit& u, const Sched& S, int wr, int wc, int fr, int fq) const {
;     ...
;         if (kind == 0) {
;             bf16_t* base = (bf16_t*)uo;
; #pragma unroll
;             for (int ai = 0; ai < 2; ++ai)
; #pragma unroll
;                 for (int m = 0; m < 4; ++m) { bf16_t* rowp = base + (size_t)(rl0 + ai * HALF + m * 16) * ldo + cl0;
; #pragma unroll
;                     for (int bj = 0; bj < 2; ++bj) { const f32x4 v0 = acc[ai][bj][m][0], v1 = acc[ai][bj][m][1];
;                         u32x4 w; w.x = cvt_pk_bf16(v0[0], v0[1]); w.y = cvt_pk_bf16(v0[2], v0[3]); w.z = cvt_pk_bf16(v1[0], v1[1]); w.w = cvt_pk_bf16(v1[2], v1[3]);
;                         *(u32x4*)(rowp + bj * HALF) = w; } }
.Linproj_epi_nt:
	v_lshl_add_u64 v[158:159], v[136:137], 1, s[46:47]
	v_lshl_add_u64 v[156:157], v[156:157], 1, v[158:159]
	v_cvt_pk_bf16_f32 v108, v108, v109
	v_cvt_pk_bf16_f32 v109, v110, v111
	v_cvt_pk_bf16_f32 v110, v104, v105
	v_cvt_pk_bf16_f32 v111, v106, v107
	v_mad_i64_i32 v[104:105], s[4:5], s35, v138, 0
	v_cvt_pk_bf16_f32 v124, v124, v125
	v_cvt_pk_bf16_f32 v125, v126, v127
	v_cvt_pk_bf16_f32 v126, v120, v121
	v_cvt_pk_bf16_f32 v127, v122, v123
	global_store_dwordx4 v[156:157], v[108:111], off offset:256 nt
	v_cvt_pk_bf16_f32 v92, v92, v93
	v_cvt_pk_bf16_f32 v93, v94, v95
	v_lshl_add_u64 v[108:109], v[104:105], 1, v[158:159]
	v_cvt_pk_bf16_f32 v94, v88, v89
	v_cvt_pk_bf16_f32 v95, v90, v91
	v_mad_i64_i32 v[88:89], s[4:5], s35, v140, 0
	global_store_dwordx4 v[156:157], v[124:127], off nt
	v_cvt_pk_bf16_f32 v104, v116, v117
	v_cvt_pk_bf16_f32 v105, v118, v119
	v_cvt_pk_bf16_f32 v106, v112, v113
	v_cvt_pk_bf16_f32 v107, v114, v115
	global_store_dwordx4 v[108:109], v[92:95], off offset:256 nt
	v_cvt_pk_bf16_f32 v76, v76, v77
	v_cvt_pk_bf16_f32 v77, v78, v79
	v_lshl_add_u64 v[92:93], v[88:89], 1, v[158:159]
	v_cvt_pk_bf16_f32 v78, v72, v73
	v_cvt_pk_bf16_f32 v79, v74, v75
	v_mad_i64_i32 v[72:73], s[4:5], s35, v142, 0
	v_cvt_pk_bf16_f32 v68, v68, v69
	v_cvt_pk_bf16_f32 v69, v70, v71
	v_cvt_pk_bf16_f32 v70, v64, v65
	v_mad_i64_i32 v[64:65], s[4:5], s35, v144, 0
	global_store_dwordx4 v[108:109], v[104:107], off nt
	v_cvt_pk_bf16_f32 v88, v100, v101
	v_cvt_pk_bf16_f32 v89, v102, v103
	v_cvt_pk_bf16_f32 v90, v96, v97
	v_cvt_pk_bf16_f32 v91, v98, v99
	global_store_dwordx4 v[92:93], v[76:79], off offset:256 nt
	v_cvt_pk_bf16_f32 v74, v80, v81
	v_cvt_pk_bf16_f32 v75, v82, v83
	v_lshl_add_u64 v[76:77], v[72:73], 1, v[158:159]
	v_cvt_pk_bf16_f32 v72, v84, v85
	v_cvt_pk_bf16_f32 v73, v86, v87
	v_cvt_pk_bf16_f32 v71, v66, v67
	v_lshl_add_u64 v[64:65], v[64:65], 1, v[158:159]
	v_cvt_pk_bf16_f32 v44, v44, v45
	v_cvt_pk_bf16_f32 v45, v46, v47
	v_cvt_pk_bf16_f32 v46, v40, v41
	v_cvt_pk_bf16_f32 v47, v42, v43
	v_mad_i64_i32 v[40:41], s[4:5], s35, v146, 0
	global_store_dwordx4 v[92:93], v[88:91], off nt
	global_store_dwordx4 v[76:77], v[72:75], off nt
	global_store_dwordx4 v[76:77], v[68:71], off offset:256 nt
	v_cvt_pk_bf16_f32 v60, v60, v61
	v_cvt_pk_bf16_f32 v61, v62, v63
	v_cvt_pk_bf16_f32 v62, v56, v57
	v_cvt_pk_bf16_f32 v63, v58, v59
	global_store_dwordx4 v[64:65], v[44:47], off offset:256 nt
	v_cvt_pk_bf16_f32 v28, v28, v29
	v_cvt_pk_bf16_f32 v29, v30, v31
	v_lshl_add_u64 v[44:45], v[40:41], 1, v[158:159]
	v_cvt_pk_bf16_f32 v30, v24, v25
	v_cvt_pk_bf16_f32 v31, v26, v27
	v_mad_i64_i32 v[24:25], s[4:5], s35, v148, 0
	global_store_dwordx4 v[64:65], v[60:63], off nt
	v_cvt_pk_bf16_f32 v40, v52, v53
	v_cvt_pk_bf16_f32 v41, v54, v55
	v_cvt_pk_bf16_f32 v42, v48, v49
	v_cvt_pk_bf16_f32 v43, v50, v51
	global_store_dwordx4 v[44:45], v[28:31], off offset:256 nt
	v_cvt_pk_bf16_f32 v12, v12, v13
	v_cvt_pk_bf16_f32 v13, v14, v15
	v_lshl_add_u64 v[28:29], v[24:25], 1, v[158:159]
	v_cvt_pk_bf16_f32 v14, v8, v9
	v_cvt_pk_bf16_f32 v15, v10, v11
	v_mad_i64_i32 v[8:9], s[4:5], s35, v150, 0
	global_store_dwordx4 v[44:45], v[40:43], off nt
	v_cvt_pk_bf16_f32 v24, v36, v37
	v_cvt_pk_bf16_f32 v25, v38, v39
	v_cvt_pk_bf16_f32 v26, v32, v33
	v_cvt_pk_bf16_f32 v27, v34, v35
	global_store_dwordx4 v[28:29], v[12:15], off offset:256 nt
	v_cvt_pk_bf16_f32 v10, v16, v17
	v_cvt_pk_bf16_f32 v11, v18, v19
	v_lshl_add_u64 v[12:13], v[8:9], 1, v[158:159]
	v_cvt_pk_bf16_f32 v8, v20, v21
	v_cvt_pk_bf16_f32 v9, v22, v23
	v_cvt_pk_bf16_f32 v4, v4, v5
	v_cvt_pk_bf16_f32 v5, v6, v7
	v_cvt_pk_bf16_f32 v6, v0, v1
	v_cvt_pk_bf16_f32 v7, v2, v3
	global_store_dwordx4 v[28:29], v[24:27], off nt
	global_store_dwordx4 v[12:13], v[8:11], off nt
	global_store_dwordx4 v[12:13], v[4:7], off offset:256 nt
	s_branch .LBB0_292
